# P3: sample-unit per-head parameter load issued early; combine loop loads both decay scalars of an iteration together
# speedup vs baseline: 1.0004x; 1.0004x over previous
.LBB0_447:
	s_add_i32 s14, s31, s34
	s_add_i32 s14, s14, -2
	s_ashr_i32 s15, s14, 31
	s_lshl_b64 s[14:15], s[14:15], 2
	s_add_u32 s28, s23, s14
	s_addc_u32 s29, s30, s15
	global_load_dword v61, v3, s[28:29]
	global_load_dword v193, v3, s[28:29] offset:4
	s_cmp_ge_u32 s34, s35
	s_cselect_b64 s[14:15], -1, 0
	s_and_b64 vcc, exec, s[14:15]
	s_waitcnt vmcnt(8)
	v_mov_b64_e32 v[80:81], v[112:113]
	s_waitcnt vmcnt(7)
	v_mov_b64_e32 v[82:83], v[110:111]
	s_waitcnt vmcnt(6)
	v_mov_b64_e32 v[86:87], v[108:109]
	s_waitcnt vmcnt(5)
	v_mov_b64_e32 v[88:89], v[106:107]
	s_waitcnt vmcnt(4)
	v_mov_b64_e32 v[90:91], v[104:105]
	s_waitcnt vmcnt(3)
	v_mov_b64_e32 v[92:93], v[102:103]
	s_waitcnt vmcnt(2)
	v_mov_b64_e32 v[94:95], v[100:101]
	s_waitcnt vmcnt(1)
	v_mov_b64_e32 v[96:97], v[98:99]
	s_cbranch_vccnz .LBB0_449
	v_add_co_u32_e32 v96, vcc, 0x8000, v62
	s_nop 1
	v_addc_co_u32_e32 v97, vcc, 0, v63, vcc
	global_load_dwordx2 v[80:81], v[96:97], off
	global_load_dwordx2 v[82:83], v[96:97], off offset:512
	global_load_dwordx2 v[86:87], v[96:97], off offset:1024
	global_load_dwordx2 v[88:89], v[96:97], off offset:1536
	global_load_dwordx2 v[90:91], v[96:97], off offset:2048
	global_load_dwordx2 v[92:93], v[96:97], off offset:2560
	global_load_dwordx2 v[94:95], v[96:97], off offset:3072
	s_nop 0
	global_load_dwordx2 v[96:97], v[96:97], off offset:3584
.LBB0_449:
	s_waitcnt vmcnt(0)
	v_mul_f32_e32 v61, 0x3fb8aa3b, v61
	v_exp_f32_e32 v120, v61
	v_lshlrev_b32_e32 v122, 16, v112
	v_and_b32_e32 v123, 0xffff0000, v112
	v_lshlrev_b32_e32 v112, 16, v113
	v_and_b32_e32 v113, 0xffff0000, v113
	v_pk_fma_f32 v[30:31], v[30:31], v[120:121], v[112:113] op_sel_hi:[1,0,1]
	v_lshlrev_b32_e32 v112, 16, v110
	v_and_b32_e32 v113, 0xffff0000, v110
	v_lshlrev_b32_e32 v110, 16, v111
	v_and_b32_e32 v111, 0xffff0000, v111
	v_pk_fma_f32 v[46:47], v[46:47], v[120:121], v[110:111] op_sel_hi:[1,0,1]
	v_lshlrev_b32_e32 v110, 16, v108
	v_and_b32_e32 v111, 0xffff0000, v108
	v_lshlrev_b32_e32 v108, 16, v109
	v_and_b32_e32 v109, 0xffff0000, v109
	v_pk_fma_f32 v[50:51], v[50:51], v[120:121], v[108:109] op_sel_hi:[1,0,1]
	v_lshlrev_b32_e32 v108, 16, v106
	v_and_b32_e32 v109, 0xffff0000, v106
	v_lshlrev_b32_e32 v106, 16, v107
	v_and_b32_e32 v107, 0xffff0000, v107
	v_pk_fma_f32 v[58:59], v[58:59], v[120:121], v[106:107] op_sel_hi:[1,0,1]
	v_lshlrev_b32_e32 v106, 16, v104
	v_and_b32_e32 v107, 0xffff0000, v104
	v_lshlrev_b32_e32 v104, 16, v105
	v_and_b32_e32 v105, 0xffff0000, v105
	v_pk_fma_f32 v[34:35], v[34:35], v[120:121], v[104:105] op_sel_hi:[1,0,1]
	v_lshlrev_b32_e32 v104, 16, v102
	v_and_b32_e32 v105, 0xffff0000, v102
	v_lshlrev_b32_e32 v102, 16, v103
	v_and_b32_e32 v103, 0xffff0000, v103
	v_pk_fma_f32 v[42:43], v[42:43], v[120:121], v[102:103] op_sel_hi:[1,0,1]
	v_lshlrev_b32_e32 v102, 16, v100
	v_and_b32_e32 v103, 0xffff0000, v100
	v_lshlrev_b32_e32 v100, 16, v101
	v_and_b32_e32 v101, 0xffff0000, v101
	v_pk_fma_f32 v[38:39], v[38:39], v[120:121], v[100:101] op_sel_hi:[1,0,1]
	v_lshlrev_b32_e32 v100, 16, v98
	v_and_b32_e32 v101, 0xffff0000, v98
	v_lshlrev_b32_e32 v98, 16, v99
	v_and_b32_e32 v99, 0xffff0000, v99
	v_pk_fma_f32 v[28:29], v[28:29], v[120:121], v[122:123] op_sel_hi:[1,0,1]
	v_pk_fma_f32 v[44:45], v[44:45], v[120:121], v[112:113] op_sel_hi:[1,0,1]
	v_pk_fma_f32 v[48:49], v[48:49], v[120:121], v[110:111] op_sel_hi:[1,0,1]
	v_pk_fma_f32 v[56:57], v[56:57], v[120:121], v[108:109] op_sel_hi:[1,0,1]
	v_pk_fma_f32 v[32:33], v[32:33], v[120:121], v[106:107] op_sel_hi:[1,0,1]
	v_pk_fma_f32 v[40:41], v[40:41], v[120:121], v[104:105] op_sel_hi:[1,0,1]
	v_pk_fma_f32 v[36:37], v[36:37], v[120:121], v[102:103] op_sel_hi:[1,0,1]
	v_pk_fma_f32 v[54:55], v[54:55], v[120:121], v[98:99] op_sel_hi:[1,0,1]
	s_andn2_b64 vcc, exec, s[16:17]
	v_pk_fma_f32 v[52:53], v[52:53], v[120:121], v[100:101] op_sel_hi:[1,0,1]
	s_cbranch_vccnz .LBB0_451
	v_lshlrev_b32_e32 v100, 16, v74
	v_and_b32_e32 v101, 0xffff0000, v74
	v_lshlrev_b32_e32 v102, 16, v75
	v_and_b32_e32 v103, 0xffff0000, v75
	v_mul_f32_e32 v61, 0x3fb8aa3b, v193
	v_exp_f32_e32 v98, v61
	s_nop 0
	v_pk_fma_f32 v[30:31], v[30:31], v[98:99], v[102:103] op_sel_hi:[1,0,1]
	v_pk_fma_f32 v[28:29], v[28:29], v[98:99], v[100:101] op_sel_hi:[1,0,1]
	v_lshlrev_b32_e32 v100, 16, v72
	v_and_b32_e32 v101, 0xffff0000, v72
	v_lshlrev_b32_e32 v102, 16, v73
	v_and_b32_e32 v103, 0xffff0000, v73
	v_pk_fma_f32 v[46:47], v[46:47], v[98:99], v[102:103] op_sel_hi:[1,0,1]
	v_pk_fma_f32 v[44:45], v[44:45], v[98:99], v[100:101] op_sel_hi:[1,0,1]
	v_lshlrev_b32_e32 v100, 16, v70
	v_and_b32_e32 v101, 0xffff0000, v70
	v_lshlrev_b32_e32 v102, 16, v71
	v_and_b32_e32 v103, 0xffff0000, v71
	v_pk_fma_f32 v[50:51], v[50:51], v[98:99], v[102:103] op_sel_hi:[1,0,1]
	v_pk_fma_f32 v[48:49], v[48:49], v[98:99], v[100:101] op_sel_hi:[1,0,1]
	v_lshlrev_b32_e32 v100, 16, v68
	v_and_b32_e32 v101, 0xffff0000, v68
	v_lshlrev_b32_e32 v102, 16, v69
	v_and_b32_e32 v103, 0xffff0000, v69
	v_pk_fma_f32 v[58:59], v[58:59], v[98:99], v[102:103] op_sel_hi:[1,0,1]
	v_pk_fma_f32 v[56:57], v[56:57], v[98:99], v[100:101] op_sel_hi:[1,0,1]
	v_lshlrev_b32_e32 v100, 16, v66
	v_and_b32_e32 v101, 0xffff0000, v66
	v_lshlrev_b32_e32 v102, 16, v67
	v_and_b32_e32 v103, 0xffff0000, v67
	v_pk_fma_f32 v[34:35], v[34:35], v[98:99], v[102:103] op_sel_hi:[1,0,1]
	v_pk_fma_f32 v[32:33], v[32:33], v[98:99], v[100:101] op_sel_hi:[1,0,1]
	v_lshlrev_b32_e32 v100, 16, v64
	v_and_b32_e32 v101, 0xffff0000, v64
	v_lshlrev_b32_e32 v102, 16, v65
	v_and_b32_e32 v103, 0xffff0000, v65
	v_pk_fma_f32 v[42:43], v[42:43], v[98:99], v[102:103] op_sel_hi:[1,0,1]
	v_pk_fma_f32 v[40:41], v[40:41], v[98:99], v[100:101] op_sel_hi:[1,0,1]
	v_lshlrev_b32_e32 v100, 16, v76
	v_and_b32_e32 v101, 0xffff0000, v76
	v_lshlrev_b32_e32 v102, 16, v77
	v_and_b32_e32 v103, 0xffff0000, v77
	v_pk_fma_f32 v[38:39], v[38:39], v[98:99], v[102:103] op_sel_hi:[1,0,1]
	v_pk_fma_f32 v[36:37], v[36:37], v[98:99], v[100:101] op_sel_hi:[1,0,1]
	v_lshlrev_b32_e32 v100, 16, v78
	v_and_b32_e32 v101, 0xffff0000, v78
	v_lshlrev_b32_e32 v102, 16, v79
	v_and_b32_e32 v103, 0xffff0000, v79
	v_pk_fma_f32 v[54:55], v[54:55], v[98:99], v[102:103] op_sel_hi:[1,0,1]
	v_pk_fma_f32 v[52:53], v[52:53], v[98:99], v[100:101] op_sel_hi:[1,0,1]

.LBB0_475:
	v_readlane_b32 s76, v254, 37
	s_waitcnt lgkmcnt(0)
	s_barrier
	v_readlane_b32 s14, v253, 41
	v_readlane_b32 s77, v254, 38
	v_mov_b32_e32 v63, v0
	v_readlane_b32 s15, v253, 42
	v_readlane_b32 s72, v254, 41
	v_readlane_b32 s80, v254, 43
	v_readlane_b32 s76, v254, 45
	v_readlane_b32 s68, v254, 59
	s_andn2_b64 vcc, exec, s[14:15]
	v_readfirstlane_b32 s18, v63
	v_readlane_b32 s83, v255, 0
	v_readlane_b32 s78, v254, 39
	v_readlane_b32 s79, v254, 40
	v_readlane_b32 s73, v254, 42
	v_readlane_b32 s81, v254, 44
	v_readlane_b32 s77, v254, 46
	v_readlane_b32 s84, v254, 63
	v_readlane_b32 s74, v254, 47
	v_readlane_b32 s30, v253, 45
	v_readlane_b32 s75, v254, 48
	v_readlane_b32 s82, v254, 49
	s_movk_i32 s85, 0x100
	s_mov_b32 s86, 0x10000
	s_mov_b32 s87, 0x18000
	s_movk_i32 s71, 0xa0
	v_readlane_b32 s69, v254, 60
	v_readlane_b32 s31, v255, 1
	s_cbranch_vccnz .LBB0_489
	s_ashr_i32 s17, s18, 8
	s_load_dwordx2 s[24:25], s[12:13], 0x60
	s_load_dwordx2 s[26:27], s[12:13], 0x28
	s_load_dwordx2 s[100:101], s[12:13], 0x68
	s_add_i32 s22, s17, s30
	s_add_i32 s14, s22, s31
	s_ashr_i32 s15, s14, 31
	s_bfe_u32 s16, s18, 0x20006
	s_lshl_b64 s[14:15], s[14:15], 2
	s_waitcnt lgkmcnt(0)
	s_add_u32 s14, s24, s14
	s_addc_u32 s15, s25, s15
	global_load_dword v7, v3, s[14:15]
	s_or_b32 s40, s31, s30
	s_ashr_i32 s41, s40, 31
	s_lshl_b64 s[40:41], s[40:41], 2
	s_add_u32 s40, s100, s40
	s_addc_u32 s41, s101, s41
	global_load_dwordx2 v[58:59], v3, s[40:41]
	v_readlane_b32 s14, v253, 2
	s_add_i32 s24, s31, s14
	s_ashr_i32 s25, s24, 31
	s_ashr_i32 s23, s22, 31
	s_lshl_b64 s[14:15], s[24:25], 10
	s_lshl_b64 s[28:29], s[22:23], 6
	s_add_u32 s19, s28, s14
	s_addc_u32 s15, s29, s15
	s_lshl_b32 s14, s16, 4
	v_and_b32_e32 v65, 15, v63
	s_or_b32 s19, s19, s14
	v_or_b32_e32 v4, s19, v65
	v_mov_b32_e32 v5, s15
	v_lshlrev_b64 v[4:5], 9, v[4:5]
	v_lshl_add_u64 v[4:5], s[26:27], 0, v[4:5]
	v_and_b32_e32 v60, 48, v63
	v_mov_b32_e32 v61, v3
	v_lshl_add_u64 v[4:5], v[4:5], 0, v[60:61]
	v_lshrrev_b32_e32 v1, 4, v63
	v_readlane_b32 s15, v253, 43
	global_load_dwordx4 v[8:11], v[4:5], off
	global_load_dwordx4 v[12:15], v[4:5], off offset:64
	global_load_dwordx4 v[16:19], v[4:5], off offset:128
	global_load_dwordx4 v[20:23], v[4:5], off offset:192
	global_load_dwordx4 v[24:27], v[4:5], off offset:256
	global_load_dwordx4 v[28:31], v[4:5], off offset:320
	global_load_dwordx4 v[32:35], v[4:5], off offset:384
	global_load_dwordx4 v[36:39], v[4:5], off offset:448
	v_and_or_b32 v1, v1, 15, s15
	v_mov_b64_e32 v[4:5], s[20:21]
	v_mad_i64_i32 v[4:5], s[20:21], v1, s95, v[4:5]
	v_lshlrev_b32_e32 v1, 3, v65
	v_readlane_b32 s15, v253, 44
	s_cmp_eq_u32 s16, 0
	s_cselect_b64 s[26:27], -1, 0
	v_or_b32_e32 v6, s15, v1
	v_readlane_b32 s15, v253, 46
	s_cmp_lg_u32 s16, 0
	s_cselect_b64 s[20:21], -1, 0
	v_or_b32_e32 v1, s15, v1
	v_lshlrev_b32_e32 v2, 1, v1
	v_lshl_add_u64 v[40:41], v[4:5], 0, v[2:3]
	v_lshlrev_b32_e32 v2, 1, v6
	v_lshl_add_u64 v[4:5], v[4:5], 0, v[2:3]
	global_load_dwordx4 v[52:55], v[40:41], off
	global_load_dwordx4 v[48:51], v[4:5], off offset:2048
	global_load_dwordx4 v[44:47], v[4:5], off offset:2560
	v_and_b32_e32 v6, 63, v63
	v_mov_b32_e32 v2, 0
	s_and_b64 vcc, exec, s[20:21]
	s_cbranch_vccnz .LBB0_478
	v_readlane_b32 s15, v253, 43
	v_readlane_b32 s28, v255, 7
	v_readlane_b32 s29, v255, 8
	v_or_b32_e32 v4, s15, v65
	v_ashrrev_i32_e32 v5, 31, v4
	v_lshlrev_b64 v[4:5], 6, v[4:5]
	v_lshl_add_u64 v[4:5], s[28:29], 0, v[4:5]
	v_lshl_add_u64 v[4:5], s[22:23], 2, v[4:5]
	global_load_dword v1, v[4:5], off
	v_cmp_gt_u32_e32 vcc, 16, v6
	s_waitcnt vmcnt(0)
	s_nop 0
	v_cndmask_b32_e32 v2, 0, v1, vcc
.LBB0_478:
	s_mul_i32 s15, s17, 0x4400
	s_or_b32 s28, s31, s30
	s_load_dwordx2 s[30:31], s[12:13], 0x68
	v_bfe_u32 v70, v63, 4, 2
	s_add_i32 s15, s15, 0
	v_or_b32_e32 v61, s14, v65
	s_add_i32 s15, s15, 0x17400
	v_mul_u32_u24_e32 v56, 0x110, v61
	v_lshlrev_b32_e32 v1, 3, v70
	v_add3_u32 v42, s15, v56, v1
	s_waitcnt vmcnt(10)
	v_cvt_pk_bf16_f32 v4, v8, v9
	v_cvt_pk_bf16_f32 v5, v10, v11
	s_waitcnt vmcnt(9)
	v_cvt_pk_bf16_f32 v40, v12, v13
	v_cvt_pk_bf16_f32 v41, v14, v15
	s_ashr_i32 s29, s28, 31
	ds_write2_b64 v42, v[4:5], v[40:41] offset1:4
	s_waitcnt vmcnt(8)
	v_cvt_pk_bf16_f32 v4, v16, v17
	v_cvt_pk_bf16_f32 v5, v18, v19
	s_waitcnt vmcnt(7)
	v_cvt_pk_bf16_f32 v40, v20, v21
	v_cvt_pk_bf16_f32 v41, v22, v23
	s_lshl_b64 s[28:29], s[28:29], 2
	ds_write2_b64 v42, v[4:5], v[40:41] offset0:8 offset1:12
	s_waitcnt vmcnt(6)
	v_cvt_pk_bf16_f32 v4, v24, v25
	v_cvt_pk_bf16_f32 v5, v26, v27
	s_waitcnt vmcnt(5)
	v_cvt_pk_bf16_f32 v40, v28, v29
	v_cvt_pk_bf16_f32 v41, v30, v31
	s_waitcnt lgkmcnt(0)
	s_add_u32 s28, s30, s28
	ds_write2_b64 v42, v[4:5], v[40:41] offset0:16 offset1:20
	s_waitcnt vmcnt(4)
	v_cvt_pk_bf16_f32 v4, v32, v33
	v_cvt_pk_bf16_f32 v5, v34, v35
	s_waitcnt vmcnt(3)
	v_cvt_pk_bf16_f32 v40, v36, v37
	v_cvt_pk_bf16_f32 v41, v38, v39
	s_addc_u32 s29, s31, s29
	ds_write2_b64 v42, v[4:5], v[40:41] offset0:24 offset1:28
	s_nop 0
	v_cndmask_b32_e64 v40, 0, 1, s[26:27]
	v_cmp_ne_u32_e64 s[38:39], 1, v40
	s_andn2_b64 vcc, exec, s[26:27]
	s_cbranch_vccnz .LBB0_480
	v_mul_f32_e32 v7, 0x3fb8aa3b, v7
	v_exp_f32_e32 v7, v7
	v_cmp_ne_u32_e32 vcc, 0, v6
	s_mul_i32 s26, s17, 0x600
	s_add_i32 s26, s26, 0
	v_subbrev_co_u32_e64 v41, s[40:41], 0, v6, vcc
	v_mul_f32_e64 v40, v2, -v7
	v_lshlrev_b32_e32 v41, 2, v41
	ds_bpermute_b32 v41, v41, v40
	s_waitcnt lgkmcnt(0)
	v_fma_f32 v7, v2, -v7, v41
	v_cndmask_b32_e32 v7, v40, v7, vcc
	v_cmp_gt_u32_e32 vcc, 2, v6
	s_nop 1
	v_cndmask_b32_e64 v40, v226, 0, vcc
	v_add_lshl_u32 v40, v40, v6, 2
	ds_bpermute_b32 v40, v40, v7
	s_waitcnt lgkmcnt(0)
	v_add_f32_e32 v40, v7, v40
	v_cndmask_b32_e32 v7, v40, v7, vcc
	v_cmp_gt_u32_e32 vcc, 4, v6
	s_nop 1
	v_cndmask_b32_e64 v40, v227, 0, vcc
	v_add_lshl_u32 v40, v40, v6, 2
	ds_bpermute_b32 v40, v40, v7
	s_waitcnt lgkmcnt(0)
	v_add_f32_e32 v40, v7, v40
	v_cndmask_b32_e32 v7, v40, v7, vcc
	v_cmp_gt_u32_e32 vcc, 8, v6
	s_nop 1
	v_cndmask_b32_e64 v40, v228, 0, vcc
	v_add_lshl_u32 v40, v40, v6, 2
	ds_bpermute_b32 v40, v40, v7
	s_waitcnt lgkmcnt(0)
	v_add_f32_e32 v40, v7, v40
	v_cndmask_b32_e32 v7, v40, v7, vcc
	v_cmp_gt_u32_e32 vcc, 16, v6
	s_nop 1
	v_cndmask_b32_e64 v40, v229, 0, vcc
	v_add_lshl_u32 v40, v40, v6, 2
	ds_bpermute_b32 v40, v40, v7
	s_waitcnt lgkmcnt(0)
	v_add_f32_e32 v40, v7, v40
	v_cndmask_b32_e32 v7, v40, v7, vcc
	v_cmp_gt_u32_e32 vcc, 32, v6
	s_nop 1
	v_cndmask_b32_e64 v40, v230, 0, vcc
	v_add_lshl_u32 v40, v40, v6, 2
	ds_bpermute_b32 v40, v40, v7
	s_waitcnt lgkmcnt(0)
	v_add_f32_e32 v40, v7, v40
	v_cndmask_b32_e32 v7, v40, v7, vcc
	v_lshl_add_u32 v40, v6, 2, s26
	v_readlane_b32 s19, v7, 63
	v_add_u32_e32 v40, 0x1fc00, v40
	ds_write2st64_b32 v40, v2, v7 offset1:1
	v_sub_f32_e32 v7, s19, v7
	v_mul_f32_e32 v7, 0x3fb8aa3b, v7
	v_exp_f32_e32 v7, v7
	s_nop 0
	v_mul_f32_e32 v2, v2, v7
	ds_write_b32 v40, v2 offset:512
.LBB0_480:
	s_mul_i32 s28, s17, 0x2800
	s_mulk_i32 s17, 0x2400
	s_add_i32 s17, s17, 0
	s_mul_i32 s30, s16, 0x900
	s_ashr_i32 s26, s18, 6
	s_lshl_b32 s18, s22, 6
	s_add_i32 s17, s17, s30
	s_add_i32 s27, 0, 0x20200
	s_ashr_i32 s19, s18, 31
	s_add_i32 s29, s28, 0
	s_lshl_b32 s28, s14, 1
	s_add_i32 s17, s17, 0x12c00
	s_cmp_lt_u32 s26, 4
	s_cselect_b64 vcc, -1, 0
	s_and_b64 s[30:31], vcc, exec
	v_lshrrev_b32_e32 v73, 2, v6
	v_readlane_b32 s30, v253, 43
	s_waitcnt vmcnt(0)
	v_cndmask_b32_e32 v71, v59, v58, vcc
	v_lshlrev_b32_e32 v7, 4, v63
	v_or_b32_e32 v72, s30, v73
	v_readlane_b32 s30, v255, 2
	v_readlane_b32 s31, v255, 3
	v_and_b32_e32 v2, 48, v7
	v_lshlrev_b32_e32 v2, 1, v2
	v_mov_b64_e32 v[4:5], s[30:31]
	v_mad_i64_i32 v[4:5], s[30:31], v72, s95, v[4:5]
	v_lshl_add_u64 v[4:5], s[18:19], 1, v[4:5]
	v_lshl_add_u64 v[40:41], v[4:5], 0, v[2:3]
	v_lshrrev_b32_e32 v4, 3, v65
	v_readlane_b32 s35, v255, 4
	v_mov_b32_e32 v5, s27
	v_cmp_gt_u32_e32 vcc, 8, v65
	v_mov_b32_e32 v42, s35
	v_mul_u32_u24_e32 v4, 0x1400, v4
	v_cndmask_b32_e32 v57, v5, v42, vcc
	v_lshlrev_b32_e32 v4, 1, v4
	v_and_b32_e32 v5, 0x70, v7
	v_add3_u32 v62, 0, v4, v5
	v_and_b32_e32 v76, 12, v73
	v_lshrrev_b32_e32 v4, 2, v63
	v_and_or_b32 v59, v4, 3, v76
	v_mul_u32_u24_e32 v4, 0x50, v59
	v_lshl_add_u32 v75, v4, 1, s29
	v_lshlrev_b32_e32 v4, 2, v6
	v_ashrrev_i32_e32 v77, 4, v63
	s_waitcnt lgkmcnt(0)
	s_barrier
	v_and_b32_e32 v4, 12, v4
	v_lshl_add_u32 v64, v77, 2, v57
	v_lshlrev_b32_e32 v74, 1, v4
	global_load_dwordx4 v[4:7], v[40:41], off offset:16
	s_nop 0
	global_load_dwordx4 v[40:43], v[40:41], off
	ds_read_b32 v64, v64 offset:512
	v_cmp_lt_i32_e32 vcc, 15, v77
	v_mad_u64_u32 v[78:79], s[30:31], v77, s71, v[62:63]
	s_nop 0
	v_cndmask_b32_e64 v66, v52, 0, vcc
	v_lshlrev_b32_e32 v80, 16, v66
	v_and_b32_e32 v81, 0xffff0000, v66
	v_cndmask_b32_e64 v69, v55, 0, vcc
	v_cndmask_b32_e64 v68, v54, 0, vcc
	v_cndmask_b32_e64 v67, v53, 0, vcc
	s_waitcnt lgkmcnt(0)
	v_pk_mul_f32 v[80:81], v[64:65], v[80:81] op_sel_hi:[0,1]
	ds_write_b128 v78, v[66:69] offset:35840
	v_cvt_pk_bf16_f32 v66, v80, v81
	v_lshlrev_b32_e32 v80, 16, v67
	v_and_b32_e32 v81, 0xffff0000, v67
	v_pk_mul_f32 v[80:81], v[64:65], v[80:81] op_sel_hi:[0,1]
	v_cvt_pk_bf16_f32 v67, v80, v81
	v_lshlrev_b32_e32 v80, 16, v68
	v_and_b32_e32 v81, 0xffff0000, v68
	v_pk_mul_f32 v[80:81], v[64:65], v[80:81] op_sel_hi:[0,1]
	v_cvt_pk_bf16_f32 v68, v80, v81
	v_lshlrev_b32_e32 v80, 16, v69
	v_and_b32_e32 v81, 0xffff0000, v69
	v_pk_mul_f32 v[80:81], v[64:65], v[80:81] op_sel_hi:[0,1]
	v_cvt_pk_bf16_f32 v69, v80, v81
	v_add_u32_e32 v64, 0x200, v63
	ds_write_b128 v78, v[66:69] offset:56320
	v_ashrrev_i32_e32 v78, 4, v64
	v_lshl_add_u32 v57, v78, 2, v57
	ds_read_b32 v64, v57 offset:512
	v_cmp_lt_i32_e64 s[40:41], 15, v78
	v_mad_u64_u32 v[66:67], s[30:31], v78, s71, v[62:63]
	s_nop 0
	v_cndmask_b32_e64 v52, v52, 0, s[40:41]
	v_lshlrev_b32_e32 v68, 16, v52
	v_and_b32_e32 v69, 0xffff0000, v52
	v_cndmask_b32_e64 v55, v55, 0, s[40:41]
	v_cndmask_b32_e64 v54, v54, 0, s[40:41]
	v_cndmask_b32_e64 v53, v53, 0, s[40:41]
	s_waitcnt lgkmcnt(0)
	v_pk_mul_f32 v[68:69], v[64:65], v[68:69] op_sel_hi:[0,1]
	ds_write_b128 v66, v[52:55] offset:35840
	v_cvt_pk_bf16_f32 v52, v68, v69
	v_lshlrev_b32_e32 v68, 16, v53
	v_and_b32_e32 v69, 0xffff0000, v53
	v_pk_mul_f32 v[68:69], v[64:65], v[68:69] op_sel_hi:[0,1]
	v_cvt_pk_bf16_f32 v53, v68, v69
	v_lshlrev_b32_e32 v68, 16, v54
	v_and_b32_e32 v69, 0xffff0000, v54
	v_pk_mul_f32 v[68:69], v[64:65], v[68:69] op_sel_hi:[0,1]
	v_cvt_pk_bf16_f32 v54, v68, v69
	v_lshlrev_b32_e32 v68, 16, v55
	v_and_b32_e32 v69, 0xffff0000, v55
	v_pk_mul_f32 v[68:69], v[64:65], v[68:69] op_sel_hi:[0,1]
	v_lshl_add_u32 v58, v65, 4, 0
	v_cvt_pk_bf16_f32 v55, v68, v69
	s_movk_i32 s34, 0x120
	ds_write_b128 v66, v[52:55] offset:56320
	v_cndmask_b32_e64 v55, v51, 0, vcc
	v_cndmask_b32_e64 v54, v50, 0, vcc
	v_cndmask_b32_e64 v53, v49, 0, vcc
	v_cndmask_b32_e64 v52, v48, 0, vcc
	v_mad_u64_u32 v[66:67], s[30:31], v77, s34, v[58:59]
	ds_write_b128 v66, v[52:55] offset:17408
	v_cndmask_b32_e64 v51, v51, 0, s[40:41]
	v_cndmask_b32_e64 v50, v50, 0, s[40:41]
	v_cndmask_b32_e64 v49, v49, 0, s[40:41]
	v_cndmask_b32_e64 v48, v48, 0, s[40:41]
	v_mad_u64_u32 v[52:53], s[30:31], v78, s34, v[58:59]
	s_movk_i32 s29, 0x110
	ds_write_b128 v52, v[48:51] offset:17408
	v_cndmask_b32_e64 v51, v47, 0, vcc
	v_cndmask_b32_e64 v50, v46, 0, vcc
	v_cndmask_b32_e64 v49, v45, 0, vcc
	v_cndmask_b32_e64 v48, v44, 0, vcc
	v_mad_u64_u32 v[52:53], s[30:31], v77, s29, v[58:59]
	ds_write_b128 v52, v[48:51]
	v_mad_u64_u32 v[48:49], s[30:31], v78, s29, v[58:59]
	v_cndmask_b32_e64 v47, v47, 0, s[40:41]
	v_cndmask_b32_e64 v46, v46, 0, s[40:41]
	v_cndmask_b32_e64 v45, v45, 0, s[40:41]
	v_cndmask_b32_e64 v44, v44, 0, s[40:41]
	v_readlane_b32 s29, v254, 27
	v_readlane_b32 s30, v254, 28
	ds_write_b128 v48, v[44:47]
	s_cselect_b32 s29, s29, s30
	s_waitcnt lgkmcnt(0)
	s_barrier
	v_mov_b32_e32 v44, s29
	ds_read_b32 v44, v44
	v_add_u32_e32 v77, 0x1400, v75
	v_mul_u32_u24_e32 v45, 0x120, v59
	v_add3_u32 v82, v75, s28, v74
	v_add3_u32 v48, v77, s28, v74
	s_waitcnt lgkmcnt(0)
	v_mul_f32_e32 v44, 0x3fb8aa3b, v44
	v_exp_f32_e32 v58, v44
	v_add3_u32 v57, 0, v45, v74
	ds_read_b64_tr_b16 v[44:45], v82 offset:56320
	ds_read_b64_tr_b16 v[46:47], v82 offset:58880
	ds_read_b64_tr_b16 v[52:53], v48 offset:56320
	ds_read_b64_tr_b16 v[54:55], v48 offset:58880
	ds_read_b64_tr_b16 v[50:51], v57 offset:31232
	ds_read_b64_tr_b16 v[66:67], v57 offset:17408
	ds_read_b64_tr_b16 v[78:79], v57 offset:17440
	ds_read_b64_tr_b16 v[82:83], v57 offset:17472
	ds_read_b64_tr_b16 v[86:87], v57 offset:17504
	ds_read_b64_tr_b16 v[68:69], v57 offset:22016
	ds_read_b64_tr_b16 v[80:81], v57 offset:22048
	ds_read_b64_tr_b16 v[84:85], v57 offset:22080
	ds_read_b64_tr_b16 v[88:89], v57 offset:22112
	ds_read_b64_tr_b16 v[48:49], v57 offset:26624
	ds_read_b64_tr_b16 v[90:91], v57 offset:26656
	ds_read_b64_tr_b16 v[94:95], v57 offset:26688
	ds_read_b64_tr_b16 v[98:99], v57 offset:26720
	ds_read_b64_tr_b16 v[92:93], v57 offset:31264
	ds_read_b64_tr_b16 v[96:97], v57 offset:31296
	ds_read_b64_tr_b16 v[100:101], v57 offset:31328
	v_pk_mul_f32 v[10:11], v[10:11], v[58:59] op_sel_hi:[1,0]
	v_pk_mul_f32 v[8:9], v[8:9], v[58:59] op_sel_hi:[1,0]
	v_pk_mul_f32 v[14:15], v[14:15], v[58:59] op_sel_hi:[1,0]
	v_pk_mul_f32 v[12:13], v[12:13], v[58:59] op_sel_hi:[1,0]
	v_pk_mul_f32 v[18:19], v[18:19], v[58:59] op_sel_hi:[1,0]
	v_pk_mul_f32 v[16:17], v[16:17], v[58:59] op_sel_hi:[1,0]
	v_pk_mul_f32 v[22:23], v[22:23], v[58:59] op_sel_hi:[1,0]
	v_pk_mul_f32 v[20:21], v[20:21], v[58:59] op_sel_hi:[1,0]
	s_waitcnt lgkmcnt(10)
	v_mfma_f32_16x16x32_bf16 v[8:11], v[66:69], v[44:47], v[8:11]
	v_mul_f32_e64 v26, v26, v58
	v_mul_f32_e64 v27, v27, v58
	v_pk_mul_f32 v[24:25], v[24:25], v[58:59] op_sel_hi:[1,0]
	s_waitcnt lgkmcnt(9)
	v_mfma_f32_16x16x32_bf16 v[12:15], v[78:81], v[44:47], v[12:15]
	v_mul_f32_e64 v30, v30, v58
	v_mul_f32_e64 v31, v31, v58
	v_pk_mul_f32 v[28:29], v[28:29], v[58:59] op_sel_hi:[1,0]
	v_pk_mul_f32 v[34:35], v[34:35], v[58:59] op_sel_hi:[1,0]
	s_waitcnt lgkmcnt(8)
	v_mfma_f32_16x16x32_bf16 v[16:19], v[82:85], v[44:47], v[16:19]
	v_mul_f32_e64 v32, v32, v58
	v_mul_f32_e64 v33, v33, v58
	v_pk_mul_f32 v[38:39], v[38:39], v[58:59] op_sel_hi:[1,0]
	v_pk_mul_f32 v[36:37], v[36:37], v[58:59] op_sel_hi:[1,0]
	s_waitcnt lgkmcnt(7)
	v_mfma_f32_16x16x32_bf16 v[20:23], v[86:89], v[44:47], v[20:23]
	s_cselect_b32 s27, s35, s27
	v_lshlrev_b32_e32 v64, 2, v70
	v_lshl_add_u32 v62, v61, 2, s27
	s_waitcnt lgkmcnt(6)
	v_mfma_f32_16x16x32_bf16 v[8:11], v[48:51], v[52:55], v[8:11]
	v_readlane_b32 s28, v254, 25
	v_readlane_b32 s29, v254, 26
	s_cselect_b32 s28, s28, s29
	s_waitcnt lgkmcnt(2)
	v_mfma_f32_16x16x32_bf16 v[12:15], v[90:93], v[52:55], v[12:15]
	v_cmp_gt_u32_e32 vcc, v61, v64
	s_waitcnt lgkmcnt(1)
	v_mfma_f32_16x16x32_bf16 v[16:19], v[94:97], v[52:55], v[16:19]
	s_waitcnt lgkmcnt(0)
	v_mfma_f32_16x16x32_bf16 v[20:23], v[98:101], v[52:55], v[20:23]
	ds_read_b64_tr_b16 v[50:51], v57 offset:31360
	ds_read_b64_tr_b16 v[66:67], v57 offset:17536
	ds_read_b64_tr_b16 v[78:79], v57 offset:17568
	ds_read_b64_tr_b16 v[82:83], v57 offset:17600
	ds_read_b64_tr_b16 v[86:87], v57 offset:17632
	ds_read_b64_tr_b16 v[68:69], v57 offset:22144
	ds_read_b64_tr_b16 v[80:81], v57 offset:22176
	ds_read_b64_tr_b16 v[84:85], v57 offset:22208
	ds_read_b64_tr_b16 v[88:89], v57 offset:22240
	ds_read_b64_tr_b16 v[48:49], v57 offset:26752
	ds_read_b64_tr_b16 v[90:91], v57 offset:26784
	ds_read_b64_tr_b16 v[94:95], v57 offset:26816
	ds_read_b64_tr_b16 v[98:99], v57 offset:26848
	ds_read_b64_tr_b16 v[92:93], v57 offset:31392
	ds_read_b64_tr_b16 v[96:97], v57 offset:31424
	ds_read_b64_tr_b16 v[100:101], v57 offset:31456
	s_waitcnt lgkmcnt(10)
	v_mfma_f32_16x16x32_bf16 v[24:27], v[66:69], v[44:47], v[24:27]
	v_mov_b32_e32 v57, s17
	s_waitcnt lgkmcnt(9)
	v_mfma_f32_16x16x32_bf16 v[28:31], v[78:81], v[44:47], v[28:31]
	v_mad_u32_u24 v78, v65, s94, v57
	s_waitcnt lgkmcnt(6)
	v_mfma_f32_16x16x32_bf16 v[24:27], v[48:51], v[52:55], v[24:27]
	v_lshrrev_b32_e32 v48, 1, v63
	v_and_b32_e32 v79, 24, v48
	s_waitcnt lgkmcnt(2)
	v_mfma_f32_16x16x32_bf16 v[28:31], v[90:93], v[52:55], v[28:31]
	v_lshl_add_u32 v92, v79, 1, 0
	v_mad_u32_u24 v90, v65, s34, v92
	ds_read_b128 v[66:69], v90 offset:17408
	v_mfma_f32_16x16x32_bf16 v[32:35], v[82:85], v[44:47], v[32:35]
	v_mul_u32_u24_e32 v93, 0x120, v65
	v_mfma_f32_16x16x32_bf16 v[36:39], v[86:89], v[44:47], v[36:39]
	v_add_u32_e32 v44, v92, v56
	ds_read_b128 v[48:51], v44
	ds_read_b128 v[80:83], v90 offset:17472
	s_waitcnt lgkmcnt(4)
	v_mfma_f32_16x16x32_bf16 v[32:35], v[94:97], v[52:55], v[32:35]
	s_waitcnt lgkmcnt(3)
	v_mfma_f32_16x16x32_bf16 v[36:39], v[98:101], v[52:55], v[36:39]
	ds_read_b128 v[52:55], v44 offset:64
	ds_read_b128 v[84:87], v90 offset:17536
	ds_read_b128 v[56:59], v44 offset:128
	ds_read_b128 v[44:47], v44 offset:192
	ds_read_b128 v[88:91], v90 offset:17600
	s_waitcnt lgkmcnt(6)
	v_mfma_f32_16x16x32_bf16 v[66:69], v[66:69], v[48:51], 0
	s_waitcnt lgkmcnt(4)
	v_mfma_f32_16x16x32_bf16 v[66:69], v[80:83], v[52:55], v[66:69]
	ds_read_b32 v81, v62 offset:256
	v_lshlrev_b32_e32 v62, 2, v64
	v_add_u32_e32 v80, v78, v1
	v_add_u32_e32 v1, s28, v62
	s_waitcnt lgkmcnt(3)
	v_mfma_f32_16x16x32_bf16 v[66:69], v[84:87], v[56:59], v[66:69]
	ds_read_b128 v[82:85], v1
	v_add_u32_e32 v1, s27, v62
	s_waitcnt lgkmcnt(2)
	v_mfma_f32_16x16x32_bf16 v[66:69], v[88:91], v[44:47], v[66:69]
	ds_read_b128 v[86:89], v1
	s_waitcnt lgkmcnt(1)
	v_sub_f32_e32 v1, v81, v82
	v_sub_f32_e32 v82, v81, v83
	v_mul_f32_e32 v1, 0x3fb8aa3b, v1
	v_mul_f32_e32 v82, 0x3fb8aa3b, v82
	v_exp_f32_e32 v1, v1
	v_exp_f32_e32 v82, v82
	v_or_b32_e32 v83, 1, v64
	v_mul_f32_e32 v1, v66, v1
	v_mul_f32_e32 v66, v67, v82
	s_waitcnt lgkmcnt(0)
	v_mul_f32_e32 v66, v87, v66
	v_mul_f32_e32 v1, v86, v1
	v_cndmask_b32_e32 v67, 0, v66, vcc
	v_cmp_le_u32_e32 vcc, v64, v61
	s_nop 1
	v_cndmask_b32_e32 v66, 0, v1, vcc
	v_cmp_eq_u32_e32 vcc, v83, v61
	v_sub_f32_e32 v1, v81, v84
	v_mul_f32_e32 v1, 0x3fb8aa3b, v1
	v_cndmask_b32_e32 v83, 0, v71, vcc
	v_cmp_eq_u32_e32 vcc, v64, v61
	v_or_b32_e32 v84, 3, v64
	s_nop 0
	v_cndmask_b32_e32 v82, 0, v71, vcc
	v_pk_add_f32 v[66:67], v[82:83], v[66:67]
	v_exp_f32_e32 v82, v1
	v_sub_f32_e32 v1, v81, v85
	v_mul_f32_e32 v1, 0x3fb8aa3b, v1
	v_exp_f32_e32 v83, v1
	v_or_b32_e32 v85, 2, v64
	v_cmp_le_u32_e32 vcc, v84, v61
	v_mov_b32_e32 v1, v64
	v_pk_mul_f32 v[68:69], v[68:69], v[82:83]
	s_nop 0
	v_pk_mul_f32 v[68:69], v[88:89], v[68:69]
	s_nop 0
	v_cndmask_b32_e32 v69, 0, v69, vcc
	v_cmp_le_u32_e32 vcc, v85, v61
	s_nop 1
	v_cndmask_b32_e32 v68, 0, v68, vcc
	v_cmp_eq_u32_e32 vcc, v84, v61
	s_nop 1
	v_cndmask_b32_e32 v83, 0, v71, vcc
	v_cmp_eq_u32_e32 vcc, v85, v61
	s_nop 1
	v_cndmask_b32_e32 v82, 0, v71, vcc
	v_pk_add_f32 v[68:69], v[82:83], v[68:69]
	s_andn2_b64 vcc, exec, s[20:21]
	v_cvt_pk_bf16_f32 v69, v68, v69
	v_cvt_pk_bf16_f32 v68, v66, v67
	ds_write_b64 v80, v[68:69]
	v_mov_b64_e32 v[66:67], 0
	v_add_u32_e32 v82, v92, v93
	v_mov_b64_e32 v[68:69], 0
	s_cbranch_vccnz .LBB0_655
	ds_read_b128 v[84:87], v82 offset:22016
	ds_read_b128 v[88:91], v82 offset:22080
	ds_read_b128 v[92:95], v82 offset:22144
	ds_read_b128 v[96:99], v82 offset:22208
	s_waitcnt lgkmcnt(3)
	v_mfma_f32_16x16x32_bf16 v[84:87], v[84:87], v[48:51], 0
	v_or_b32_e32 v83, 17, v1
	v_cmp_eq_u32_e64 s[40:41], v83, v61
	v_or_b32_e32 v83, 19, v1
	s_waitcnt lgkmcnt(2)
	v_mfma_f32_16x16x32_bf16 v[84:87], v[88:91], v[52:55], v[84:87]
	s_waitcnt lgkmcnt(1)
	v_mfma_f32_16x16x32_bf16 v[84:87], v[92:95], v[56:59], v[84:87]
	s_waitcnt lgkmcnt(0)
	v_mfma_f32_16x16x32_bf16 v[84:87], v[96:99], v[44:47], v[84:87]
	v_or_b32_e32 v96, 16, v64
	v_lshlrev_b32_e32 v68, 2, v96
	v_add_u32_e32 v69, s28, v68
	ds_read_b128 v[88:91], v69
	v_add_u32_e32 v68, s27, v68
	ds_read_b128 v[92:95], v68
	v_cmp_gt_u32_e32 vcc, v61, v96
	s_waitcnt lgkmcnt(1)
	v_sub_f32_e32 v69, v81, v89
	v_sub_f32_e32 v68, v81, v88
	v_mul_f32_e32 v69, 0x3fb8aa3b, v69
	v_mul_f32_e32 v68, 0x3fb8aa3b, v68
	v_exp_f32_e32 v69, v69
	v_exp_f32_e32 v68, v68
	v_or_b32_e32 v88, 18, v64
	v_mul_f32_e32 v69, v85, v69
	v_mul_f32_e32 v68, v84, v68
	s_waitcnt lgkmcnt(0)
	v_mul_f32_e32 v69, v93, v69
	v_mul_f32_e32 v68, v92, v68
	v_cndmask_b32_e32 v69, 0, v69, vcc
	v_cmp_le_u32_e32 vcc, v96, v61
	v_cndmask_b32_e64 v85, 0, v71, s[40:41]
	v_cmp_eq_u32_e64 s[40:41], v83, v61
	v_cndmask_b32_e32 v68, 0, v68, vcc
	v_cmp_eq_u32_e32 vcc, v96, v61
	s_nop 1
	v_cndmask_b32_e32 v84, 0, v71, vcc
	v_pk_add_f32 v[68:69], v[84:85], v[68:69]
	v_sub_f32_e32 v84, v81, v90
	v_sub_f32_e32 v85, v81, v91
	v_mul_f32_e32 v84, 0x3fb8aa3b, v84
	v_mul_f32_e32 v85, 0x3fb8aa3b, v85
	v_exp_f32_e32 v84, v84
	v_exp_f32_e32 v85, v85
	v_cmp_le_u32_e32 vcc, v83, v61
	v_cvt_pk_bf16_f32 v68, v68, v69
	v_pk_mul_f32 v[84:85], v[86:87], v[84:85]
	s_nop 0
	v_pk_mul_f32 v[84:85], v[94:95], v[84:85]
	v_cndmask_b32_e64 v87, 0, v71, s[40:41]
	v_cndmask_b32_e32 v85, 0, v85, vcc
	v_cmp_le_u32_e32 vcc, v88, v61
	s_nop 1
	v_cndmask_b32_e32 v84, 0, v84, vcc
	v_cmp_eq_u32_e32 vcc, v88, v61
	s_nop 1
	v_cndmask_b32_e32 v86, 0, v71, vcc
	v_pk_add_f32 v[84:85], v[86:87], v[84:85]
	s_nop 0
	v_cvt_pk_bf16_f32 v69, v84, v85
	s_cmp_lt_u32 s16, 2
	ds_write_b64 v80, v[68:69] offset:32
	s_cbranch_scc0 .LBB0_656
